# grid barriers: the acquire-side cache invalidate is issued right after the block's arrival (no loads follow it except the sc1 polls), overlapping its latency with the wait
# speedup vs baseline: 1.0146x; 1.0127x over previous
.Lxb0_poll:
	buffer_inv sc1
	s_mov_b32 s100, 0
.Lxb0_spin:
	global_load_dword v7, v6, s[98:99] sc1
	s_waitcnt vmcnt(0)
	v_cmp_ge_u32_e32 vcc, v7, v3
	s_cbranch_vccnz .Lxb0_done
	s_sleep 1
	s_add_i32 s100, s100, 1
	s_cmp_lt_u32 s100, 0x40000
	s_cbranch_scc1 .Lxb0_spin
.Lxb0_done:
	s_waitcnt vmcnt(0)

.Lxb1_spin:
	global_load_dword v7, v6, s[98:99] sc1
	s_waitcnt vmcnt(0)
	v_cmp_ge_u32_e32 vcc, v7, v3
	s_cbranch_vccnz .Lxb1_done
	s_sleep 1
	s_add_i32 s100, s100, 1
	s_cmp_lt_u32 s100, 0x40000
	s_cbranch_scc1 .Lxb1_spin
.Lxb1_done:
	s_waitcnt vmcnt(0)
.LBB0_224:
	s_or_b64 exec, exec, s[0:1]
	s_add_u32 s18, s90, 0x48f0000
	s_addc_u32 s19, s91, 0
	s_add_u32 s48, s90, 0x60000
	s_addc_u32 s49, s91, 0
	v_mov_b32_e32 v8, v193
	s_cmpk_lt_i32 s6, 0x800
	s_waitcnt lgkmcnt(0)
	s_barrier
	s_cselect_b64 s[0:1], -1, 0
	s_cmpk_gt_i32 s6, 0x7ff
	v_readfirstlane_b32 s2, v8
	s_cbranch_scc1 .LBB0_227
	s_ashr_i32 s3, s6, 31
	s_lshr_b32 s3, s3, 29
	s_add_i32 s3, s6, s3
	s_and_b32 s4, s3, -8
	s_sub_i32 s7, s6, s4
	s_cmp_gt_i32 s7, -1
	s_cbranch_scc0 .LBB0_228
	s_lshl_b32 s8, s7, 8
	s_cbranch_execz .LBB0_229
	s_branch .LBB0_230

.Lxb2_spin:
	global_load_dword v7, v6, s[98:99] sc1
	s_waitcnt vmcnt(0)
	v_cmp_ge_u32_e32 vcc, v7, v3
	s_cbranch_vccnz .Lxb2_done
	s_sleep 1
	s_add_i32 s100, s100, 1
	s_cmp_lt_u32 s100, 0x40000
	s_cbranch_scc1 .Lxb2_spin
.Lxb2_done:
	s_waitcnt vmcnt(0)
.LBB0_431:
	s_or_b64 exec, exec, s[0:1]
	s_add_u32 s22, s90, 0x198f0000
	s_addc_u32 s23, s91, 0
	v_mov_b32_e32 v9, v193
	s_waitcnt lgkmcnt(0)
	s_barrier
	s_cmpk_gt_i32 s6, 0x7f
	v_readfirstlane_b32 s10, v9
	s_cbranch_scc1 .LBB0_447
	v_lshlrev_b32_e32 v0, 4, v9
	v_add_u32_e32 v1, 0x2000, v0
	v_ashrrev_i32_e32 v2, 31, v1
	v_lshrrev_b32_e32 v2, 22, v2
	v_add_u32_e32 v2, v1, v2
	v_ashrrev_i32_e32 v8, 10, v2
	v_mul_i32_i24_e32 v2, 0x400, v8
	v_sub_u32_e32 v1, v1, v2
	v_lshrrev_b32_e32 v2, 4, v1
	v_bitop3_b32 v1, v2, v1, 32 bitop3:0x6c
	v_ashrrev_i32_e32 v2, 31, v1
	v_lshrrev_b32_e32 v2, 26, v2
	v_add_u32_e32 v2, v1, v2
	v_lshlrev_b32_e32 v3, 3, v8
	v_ashrrev_i32_e32 v10, 6, v2
	v_and_b32_e32 v3, -16, v3
	v_add_u32_e32 v3, v10, v3
	v_and_b32_e32 v4, 3, v10
	s_mov_b32 s0, 0x3fffe0
	v_lshrrev_b32_e32 v5, 2, v3
	v_lshlrev_b32_e32 v6, 1, v3
	v_and_b32_e32 v2, 0xc0, v2
	v_and_or_b32 v4, v3, s0, v4
	v_and_b32_e32 v5, 4, v5
	v_and_b32_e32 v6, 24, v6
	v_sub_u32_e32 v1, v1, v2
	v_mov_b32_e32 v2, 1
	v_or3_b32 v4, v4, v5, v6
	v_lshlrev_b32_e32 v5, 5, v8
	v_ashrrev_i16_sdwa v1, v2, sext(v1) dst_sel:DWORD dst_unused:UNUSED_PAD src0_sel:DWORD src1_sel:BYTE_0
	v_and_b32_e32 v11, 32, v5
	v_bfe_i32 v12, v1, 0, 16
	s_movk_i32 s13, 0x300
	v_add_u32_e32 v1, v11, v12
	v_mul_lo_u32 v3, v3, s13
	v_lshlrev_b32_e32 v5, 1, v1
	v_add_lshl_u32 v130, v1, v3, 1
	v_bfe_i32 v1, v9, 27, 1
	v_lshrrev_b32_e32 v1, 22, v1
	v_add_u32_e32 v1, v0, v1
	v_and_b32_e32 v1, 0xfffffc00, v1
	v_sub_u32_e32 v0, v0, v1
	v_lshrrev_b32_e32 v1, 4, v0
	v_ashrrev_i32_e32 v3, 31, v9
	v_bitop3_b32 v0, v1, v0, 32 bitop3:0x6c
	v_lshrrev_b32_e32 v3, 26, v3
	v_ashrrev_i32_e32 v1, 31, v0
	v_add_u32_e32 v3, v9, v3
	v_lshrrev_b32_e32 v1, 26, v1
	v_ashrrev_i32_e32 v14, 6, v3
	v_add_u32_e32 v1, v0, v1
	v_lshlrev_b32_e32 v3, 3, v14
	v_ashrrev_i32_e32 v13, 6, v1
	v_and_b32_e32 v3, -16, v3
	s_add_u32 s2, s90, 0x3760000
	v_lshl_add_u32 v128, v4, 10, v5
	v_add_u32_e32 v3, v13, v3
	v_and_b32_e32 v4, 3, v13
	s_addc_u32 s3, s91, 0
	v_and_or_b32 v4, v3, s0, v4
	s_ashr_i32 s0, s6, 31
	s_lshr_b32 s0, s0, 30
	s_add_i32 s0, s6, s0
	s_ashr_i32 s8, s0, 2
	s_lshl_b32 s0, s6, 8
	s_and_b32 s51, s0, 0x300
	s_ashr_i32 s9, s8, 31
	s_lshl_b64 s[0:1], s[8:9], 11
	s_lshl_b32 s5, s51, 1
	s_or_b32 s0, s0, s5
	s_ashr_i32 s4, s10, 6
	v_lshrrev_b32_e32 v5, 2, v3
	v_lshlrev_b32_e32 v6, 1, v3
	v_and_b32_e32 v1, 0xc0, v1
	s_mulk_i32 s1, 0x300
	s_mul_hi_u32 s5, s0, 0x300
	s_ashr_i32 s11, s10, 8
	s_lshl_b32 s12, s4, 10
	v_and_b32_e32 v5, 4, v5
	v_and_b32_e32 v6, 24, v6
	v_sub_u32_e32 v0, v0, v1
	s_add_i32 s5, s5, s1
	s_mulk_i32 s0, 0x300
	v_or3_b32 v4, v4, v5, v6
	v_lshlrev_b32_e32 v5, 5, v14
	v_ashrrev_i16_sdwa v0, v2, sext(v0) dst_sel:DWORD dst_unused:UNUSED_PAD src0_sel:DWORD src1_sel:BYTE_0
	s_add_u32 s38, s26, s0
	v_and_b32_e32 v15, 32, v5
	v_bfe_i32 v16, v0, 0, 16
	s_addc_u32 s39, s27, s5
	s_lshl_b64 s[0:1], s[8:9], 18
	v_add_u32_e32 v0, v15, v16
	s_add_u32 s40, s2, s0
	v_lshlrev_b32_e32 v1, 1, v0
	s_addc_u32 s41, s3, s1
	s_add_i32 s7, s12, 0
	v_lshl_add_u32 v132, v4, 10, v1
	s_add_i32 m0, s7, 0x10000
	v_mul_lo_u32 v1, v3, s13
	global_load_lds_dwordx4 v132, s[40:41]
	s_add_i32 m0, s7, 0x12000
	s_add_u32 s0, s40, 0x20000
	global_load_lds_dwordx4 v128, s[40:41]
	s_addc_u32 s1, s41, 0
	s_add_i32 m0, s7, 0x14000
	s_add_i32 s33, s7, 0x2000
	global_load_lds_dwordx4 v132, s[0:1]
	s_add_i32 m0, s7, 0x16000
	v_add_lshl_u32 v134, v0, v1, 1
	global_load_lds_dwordx4 v128, s[0:1]
	s_mov_b32 m0, s7
	s_add_u32 s0, s38, 0x30000
	global_load_lds_dwordx4 v134, s[38:39]
	s_mov_b32 m0, s33
	s_addc_u32 s1, s39, 0
	s_add_i32 s34, s7, 0x4000
	global_load_lds_dwordx4 v130, s[38:39]
	s_mov_b32 m0, s34
	s_add_i32 s35, s7, 0x6000
	global_load_lds_dwordx4 v134, s[0:1]
	s_mov_b32 m0, s35
	v_mov_b32_e32 v137, 0
	global_load_lds_dwordx4 v130, s[0:1]
	v_mov_b32_e32 v133, v137
	v_mov_b32_e32 v129, v137
	v_mov_b32_e32 v135, v137
	v_mov_b32_e32 v131, v137
	s_cmp_eq_u32 s11, 1
	s_mov_b32 s48, 0
	v_lshl_add_u64 v[6:7], s[40:41], 0, v[132:133]
	v_lshl_add_u64 v[4:5], s[40:41], 0, v[128:129]
	v_lshl_add_u64 v[0:1], s[38:39], 0, v[134:135]
	s_cselect_b64 s[0:1], -1, 0
	s_cmp_lg_u32 s11, 1
	v_lshl_add_u64 v[2:3], s[38:39], 0, v[130:131]
	s_cbranch_scc1 .LBB0_434
	s_barrier

.Lxb3_spin:
	global_load_dword v7, v6, s[98:99] sc1
	s_waitcnt vmcnt(0)
	v_cmp_ge_u32_e32 vcc, v7, v3
	s_cbranch_vccnz .Lxb3_done
	s_sleep 1
	s_add_i32 s100, s100, 1
	s_cmp_lt_u32 s100, 0x40000
	s_cbranch_scc1 .Lxb3_spin
.Lxb3_done:
	s_waitcnt vmcnt(0)
.LBB0_544:
	s_or_b64 exec, exec, s[0:1]
	s_waitcnt lgkmcnt(0)
	v_mov_b32_e32 v0, 0x6050400
	v_perm_b32 v0, s6, v193, v0
	v_and_b32_e32 v1, 0x300, v193
	v_mad_u64_u32 v[0:1], s[0:1], s92, v1, v[0:1]
	s_mov_b32 s2, 0x10000
	v_cmp_gt_i32_e32 vcc, s2, v0
	v_and_b32_e32 v192, 63, v193
	s_barrier
	s_and_saveexec_b64 s[0:1], vcc
	s_cbranch_execz .LBB0_551
	v_mov_b32_e32 v3, 0
	v_lshlrev_b32_e32 v2, 3, v192
	v_lshl_add_u64 v[4:5], s[90:91], 0, v[2:3]
	s_mov_b64 s[4:5], 0x3fe0000
	s_lshl_b32 s3, s92, 9
	v_lshl_add_u64 v[4:5], v[4:5], 0, s[4:5]
	s_mov_b64 s[4:5], 0
	s_movk_i32 s7, 0x4000
	s_movk_i32 s12, 0x3c0
	v_lshlrev_b32_e32 v6, 2, v192
	v_mov_b32_e32 v7, v3
	s_movk_i32 s13, 0x600
	v_mov_b64_e32 v[8:9], s[90:91]
	v_lshlrev_b32_e32 v10, 1, v192
	v_mov_b32_e32 v11, v3
	s_mov_b64 s[8:9], 0x88f0400
	s_movk_i32 s14, 0x1000
	s_movk_i32 s15, 0x2000
	s_movk_i32 s16, 0x3000
	s_movk_i32 s17, 0x5000
	s_movk_i32 s33, 0x6000
	s_movk_i32 s34, 0x7000
	s_mov_b32 s35, 0x8000
	s_mov_b32 s38, 0x9000
	s_mov_b32 s39, 0xa000
	s_mov_b32 s40, 0xb000
	s_mov_b32 s41, 0xc000
	s_mov_b32 s42, 0xd000
	s_mov_b32 s43, 0xe000
	s_mov_b32 s44, 0xf000
	s_mov_b32 s45, 0x17000
	s_mov_b32 s48, 0x16000
	s_mov_b32 s49, 0x15000
	s_mov_b32 s50, 0x14000
	s_mov_b32 s51, 0x13000
	s_mov_b32 s54, 0x12000
	s_mov_b32 s55, 0x11000
	s_mov_b32 s56, 0xffff
	s_branch .LBB0_547

.Lxb4_spin:
	global_load_dword v7, v6, s[98:99] sc1
	s_waitcnt vmcnt(0)
	v_cmp_ge_u32_e32 vcc, v7, v3
	s_cbranch_vccnz .Lxb4_done
	s_sleep 1
	s_add_i32 s100, s100, 1
	s_cmp_lt_u32 s100, 0x40000
	s_cbranch_scc1 .Lxb4_spin
.Lxb4_done:
	s_waitcnt vmcnt(0)
.LBB0_641:
	s_or_b64 exec, exec, s[0:1]
	v_mov_b32_e32 v9, v193
	s_cmpk_lt_i32 s6, 0x100
	s_waitcnt lgkmcnt(0)
	s_barrier
	s_cselect_b64 s[0:1], -1, 0
	s_cmpk_gt_i32 s6, 0xff
	v_readfirstlane_b32 s3, v9
	s_cbranch_scc1 .LBB0_657
	v_lshlrev_b32_e32 v0, 4, v9
	v_add_u32_e32 v1, 0x2000, v0
	v_ashrrev_i32_e32 v2, 31, v1
	v_lshrrev_b32_e32 v2, 22, v2
	v_add_u32_e32 v2, v1, v2
	v_ashrrev_i32_e32 v8, 10, v2
	v_mul_i32_i24_e32 v2, 0x400, v8
	v_sub_u32_e32 v1, v1, v2
	v_lshrrev_b32_e32 v2, 4, v1
	v_bitop3_b32 v1, v2, v1, 32 bitop3:0x6c
	v_ashrrev_i32_e32 v2, 31, v1
	v_lshrrev_b32_e32 v2, 26, v2
	v_add_u32_e32 v2, v1, v2
	v_lshlrev_b32_e32 v3, 3, v8
	v_ashrrev_i32_e32 v10, 6, v2
	v_and_b32_e32 v3, -16, v3
	v_add_u32_e32 v3, v10, v3
	v_and_b32_e32 v4, 3, v10
	s_mov_b32 s2, 0xffffe0
	v_lshrrev_b32_e32 v5, 2, v3
	v_lshlrev_b32_e32 v6, 1, v3
	v_and_b32_e32 v2, 0xc0, v2
	v_and_or_b32 v4, v3, s2, v4
	v_and_b32_e32 v5, 4, v5
	v_and_b32_e32 v6, 24, v6
	v_sub_u32_e32 v1, v1, v2
	v_mov_b32_e32 v2, 1
	v_or3_b32 v4, v4, v5, v6
	v_lshlrev_b32_e32 v5, 5, v8
	v_ashrrev_i16_sdwa v1, v2, sext(v1) dst_sel:DWORD dst_unused:UNUSED_PAD src0_sel:DWORD src1_sel:BYTE_0
	s_movk_i32 s33, 0x300
	v_and_b32_e32 v11, 32, v5
	v_bfe_i32 v12, v1, 0, 16
	v_mul_u32_u24_e32 v4, 0x300, v4
	v_add_u32_e32 v1, v11, v12
	v_mul_lo_u32 v3, v3, s33
	v_add_lshl_u32 v128, v4, v1, 1
	v_add_lshl_u32 v130, v1, v3, 1
	v_bfe_i32 v1, v9, 27, 1
	v_lshrrev_b32_e32 v1, 22, v1
	v_add_u32_e32 v1, v0, v1
	v_and_b32_e32 v1, 0xfffffc00, v1
	v_sub_u32_e32 v0, v0, v1
	v_lshrrev_b32_e32 v1, 4, v0
	v_ashrrev_i32_e32 v3, 31, v9
	v_bitop3_b32 v0, v1, v0, 32 bitop3:0x6c
	v_lshrrev_b32_e32 v3, 26, v3
	v_ashrrev_i32_e32 v1, 31, v0
	v_add_u32_e32 v3, v9, v3
	v_lshrrev_b32_e32 v1, 26, v1
	v_ashrrev_i32_e32 v14, 6, v3
	v_add_u32_e32 v1, v0, v1
	v_lshlrev_b32_e32 v3, 3, v14
	s_add_u32 s66, s90, 0x1f60000
	v_ashrrev_i32_e32 v13, 6, v1
	v_and_b32_e32 v3, -16, v3
	s_addc_u32 s67, s91, 0
	v_add_u32_e32 v3, v13, v3
	v_and_b32_e32 v4, 3, v13
	s_ashr_i32 s9, s6, 31
	v_and_or_b32 v4, v3, s2, v4
	s_lshr_b32 s2, s6, 31
	s_lshr_b32 s9, s9, 29
	s_add_i32 s2, s6, s2
	s_add_i32 s9, s6, s9
	s_and_b32 s8, s2, 0xfffffe
	s_ashr_i32 s54, s9, 3
	s_lshl_b32 s2, s2, 7
	s_sub_i32 s8, s6, s8
	s_and_b32 s2, s2, 0x300
	s_ashr_i32 s55, s54, 31
	s_lshl_b32 s56, s8, 8
	s_lshl_b64 s[8:9], s[54:55], 11
	s_lshl_b32 s11, s2, 1
	s_or_b32 s8, s8, s11
	s_ashr_i32 s10, s3, 6
	s_mulk_i32 s9, 0x300
	s_mul_hi_u32 s11, s8, 0x300
	s_ashr_i32 s7, s3, 8
	s_lshl_b32 s68, s10, 10
	s_add_i32 s11, s11, s9
	s_mulk_i32 s8, 0x300
	s_add_u32 s58, s26, s8
	s_addc_u32 s59, s27, s11
	s_ashr_i32 s57, s56, 31
	s_lshl_b64 s[8:9], s[54:55], 10
	s_lshl_b64 s[30:31], s[56:57], 1
	s_add_u32 s8, s30, s8
	v_lshrrev_b32_e32 v5, 2, v3
	v_lshlrev_b32_e32 v6, 1, v3
	v_and_b32_e32 v1, 0xc0, v1
	s_addc_u32 s9, s31, s9
	v_and_b32_e32 v5, 4, v5
	v_and_b32_e32 v6, 24, v6
	v_sub_u32_e32 v0, v0, v1
	s_mulk_i32 s9, 0x300
	s_mul_hi_u32 s11, s8, 0x300
	v_or3_b32 v4, v4, v5, v6
	v_lshlrev_b32_e32 v5, 5, v14
	v_ashrrev_i16_sdwa v0, v2, sext(v0) dst_sel:DWORD dst_unused:UNUSED_PAD src0_sel:DWORD src1_sel:BYTE_0
	s_add_i32 s11, s11, s9
	s_mulk_i32 s8, 0x300
	v_and_b32_e32 v15, 32, v5
	v_bfe_i32 v16, v0, 0, 16
	s_add_u32 s60, s66, s8
	v_mul_u32_u24_e32 v4, 0x300, v4
	v_add_u32_e32 v0, v15, v16
	s_addc_u32 s61, s67, s11
	s_add_i32 s57, s68, 0
	v_add_lshl_u32 v132, v4, v0, 1
	s_add_i32 m0, s57, 0x10000
	v_mul_lo_u32 v1, v3, s33
	global_load_lds_dwordx4 v132, s[60:61]
	s_add_i32 m0, s57, 0x12000
	s_add_u32 s8, s60, 0x30000
	global_load_lds_dwordx4 v128, s[60:61]
	s_addc_u32 s9, s61, 0
	s_add_i32 m0, s57, 0x14000
	s_add_i32 s69, s57, 0x2000
	global_load_lds_dwordx4 v132, s[8:9]
	s_add_i32 m0, s57, 0x16000
	v_add_lshl_u32 v134, v0, v1, 1
	global_load_lds_dwordx4 v128, s[8:9]
	s_mov_b32 m0, s57
	s_add_u32 s8, s58, 0x30000
	global_load_lds_dwordx4 v134, s[58:59]
	s_mov_b32 m0, s69
	s_addc_u32 s9, s59, 0
	s_add_i32 s70, s57, 0x4000
	global_load_lds_dwordx4 v130, s[58:59]
	s_mov_b32 m0, s70
	s_add_i32 s71, s57, 0x6000
	global_load_lds_dwordx4 v134, s[8:9]
	s_mov_b32 m0, s71
	v_mov_b32_e32 v137, 0
	global_load_lds_dwordx4 v130, s[8:9]
	v_mov_b32_e32 v133, v137
	v_mov_b32_e32 v129, v137
	v_mov_b32_e32 v135, v137
	v_mov_b32_e32 v131, v137
	s_cmp_eq_u32 s7, 1
	s_mov_b32 s72, 0
	v_lshl_add_u64 v[6:7], s[60:61], 0, v[132:133]
	v_lshl_add_u64 v[4:5], s[60:61], 0, v[128:129]
	v_lshl_add_u64 v[0:1], s[58:59], 0, v[134:135]
	s_cselect_b64 s[8:9], -1, 0
	s_cmp_lg_u32 s7, 1
	v_lshl_add_u64 v[2:3], s[58:59], 0, v[130:131]
	s_cbranch_scc1 .LBB0_644
	s_barrier

.Lxb5_spin:
	global_load_dword v7, v6, s[98:99] sc1
	s_waitcnt vmcnt(0)
	v_cmp_ge_u32_e32 vcc, v7, v3
	s_cbranch_vccnz .Lxb5_done
	s_sleep 1
	s_add_i32 s100, s100, 1
	s_cmp_lt_u32 s100, 0x40000
	s_cbranch_scc1 .Lxb5_spin
.Lxb5_done:
	s_waitcnt vmcnt(0)
.LBB0_709:
	s_or_b64 exec, exec, s[8:9]
	s_add_u32 s26, s90, 0x68f0000
	v_mov_b32_e32 v8, v193
	s_waitcnt lgkmcnt(0)
	s_barrier
	s_addc_u32 s27, s91, 0
	s_andn2_b64 vcc, exec, s[0:1]
	v_readfirstlane_b32 s2, v8
	s_cbranch_vccnz .LBB0_733
	s_ashr_i32 s64, s6, 31
	s_lshr_b32 s0, s64, 29
	s_add_i32 s7, s6, s0
	s_and_b32 s0, s7, -8
	s_sub_i32 s8, s6, s0
	s_cmp_gt_i32 s8, -1
	s_cbranch_scc0 .LBB0_712
	s_lshl_b32 s3, s8, 5
	s_cbranch_execz .LBB0_713
	s_branch .LBB0_714

.Lxb6_spin:
	global_load_dword v7, v6, s[98:99] sc1
	s_waitcnt vmcnt(0)
	v_cmp_ge_u32_e32 vcc, v7, v3
	s_cbranch_vccnz .Lxb6_done
	s_sleep 1
	s_add_i32 s100, s100, 1
	s_cmp_lt_u32 s100, 0x40000
	s_cbranch_scc1 .Lxb6_spin
.Lxb6_done:
	s_waitcnt vmcnt(0)
.LBB0_785:
	s_or_b64 exec, exec, s[0:1]
	v_mov_b32_e32 v8, v193
	s_waitcnt lgkmcnt(0)
	v_cndmask_b32_e64 v0, 0, 1, s[28:29]
	s_barrier
	v_cmp_ne_u32_e64 s[10:11], 1, v0
	s_andn2_b64 vcc, exec, s[28:29]
	v_readfirstlane_b32 s3, v8
	s_cbranch_vccnz .LBB0_788
	s_ashr_i32 s0, s6, 31
	s_lshr_b32 s0, s0, 29
	s_add_i32 s2, s6, s0
	s_and_b32 s0, s2, -8
	s_sub_i32 s4, s6, s0
	s_cmp_gt_i32 s4, -1
	s_cbranch_scc0 .LBB0_789
	s_lshl_b32 s5, s4, 6
	s_cbranch_execz .LBB0_790
	s_branch .LBB0_791

.Lxb7_spin:
	global_load_dword v7, v6, s[98:99] sc1
	s_waitcnt vmcnt(0)
	v_cmp_ge_u32_e32 vcc, v7, v3
	s_cbranch_vccnz .Lxb7_done
	s_sleep 1
	s_add_i32 s100, s100, 1
	s_cmp_lt_u32 s100, 0x40000
	s_cbranch_scc1 .Lxb7_spin
.Lxb7_done:
	s_waitcnt vmcnt(0)
.LBB0_961:
	s_or_b64 exec, exec, s[0:1]
	v_mov_b32_e32 v8, v193
	s_waitcnt lgkmcnt(0)
	s_barrier
	s_and_b64 vcc, exec, s[10:11]
	v_readfirstlane_b32 s24, v8
	s_cbranch_vccnz .LBB0_985
	s_ashr_i32 s2, s6, 31
	s_lshr_b32 s0, s2, 29
	s_add_i32 s3, s6, s0
	s_and_b32 s0, s3, -8
	s_sub_i32 s5, s6, s0
	s_cmp_gt_i32 s5, -1
	s_cbranch_scc0 .LBB0_964
	s_lshl_b32 s4, s5, 6
	s_cbranch_execz .LBB0_965
	s_branch .LBB0_966

.Lxb8_spin:
	global_load_dword v7, v6, s[98:99] sc1
	s_waitcnt vmcnt(0)
	v_cmp_ge_u32_e32 vcc, v7, v3
	s_cbranch_vccnz .Lxb8_done
	s_sleep 1
	s_add_i32 s100, s100, 1
	s_cmp_lt_u32 s100, 0x40000
	s_cbranch_scc1 .Lxb8_spin
.Lxb8_done:
	s_waitcnt vmcnt(0)
.LBB0_1037:
	s_or_b64 exec, exec, s[0:1]
	s_waitcnt lgkmcnt(0)
	v_lshrrev_b32_e32 v0, 5, v193
	v_and_b32_e32 v0, 30, v0
	v_lshl_add_u32 v144, s6, 4, v0
	s_mov_b32 s0, 0x8000
	v_cmp_gt_i32_e64 s[4:5], s0, v144
	v_ashrrev_i32_e32 v145, 31, v144
	s_barrier
	s_and_saveexec_b64 s[24:25], s[4:5]
	s_cbranch_execz .LBB0_1040
	v_lshlrev_b32_e32 v16, 4, v192
	global_load_dwordx4 v[0:3], v16, s[46:47]
	global_load_dwordx4 v[4:7], v16, s[46:47] offset:1024
	global_load_dwordx4 v[8:11], v16, s[46:47] offset:2048
	global_load_dwordx4 v[12:15], v16, s[46:47] offset:3072
	v_mbcnt_hi_u32_b32 v16, -1, v226
	v_and_b32_e32 v17, 64, v16
	v_add_u32_e32 v17, 64, v17
	v_xor_b32_e32 v18, 1, v16
	v_cmp_lt_i32_e32 vcc, v18, v17
	s_lshl_b32 s26, s92, 4
	v_or_b32_e32 v22, 0x80, v192
	v_cndmask_b32_e32 v18, v16, v18, vcc
	v_lshlrev_b32_e32 v44, 2, v18
	v_xor_b32_e32 v18, 2, v16
	v_cmp_lt_i32_e32 vcc, v18, v17
	v_or_b32_e32 v24, 0xc0, v192
	s_mov_b64 s[0:1], 0x198f0e00
	v_cndmask_b32_e32 v18, v16, v18, vcc
	v_lshlrev_b32_e32 v45, 2, v18
	v_xor_b32_e32 v18, 4, v16
	v_cmp_lt_i32_e32 vcc, v18, v17
	s_ashr_i32 s27, s26, 31
	s_lshl_b64 s[28:29], s[26:27], 11
	v_cndmask_b32_e32 v18, v16, v18, vcc
	v_lshlrev_b32_e32 v46, 2, v18
	v_xor_b32_e32 v18, 8, v16
	v_cmp_lt_i32_e32 vcc, v18, v17
	s_mov_b64 s[30:31], 0
	s_mov_b64 s[36:37], 0x3000
	v_cndmask_b32_e32 v18, v16, v18, vcc
	v_lshlrev_b32_e32 v47, 2, v18
	v_xor_b32_e32 v18, 16, v16
	v_cmp_lt_i32_e32 vcc, v18, v17
	s_mov_b64 s[38:39], 0x4000
	v_lshlrev_b32_e32 v20, 4, v192
	v_cndmask_b32_e32 v18, v16, v18, vcc
	v_lshlrev_b32_e32 v48, 2, v18
	v_xor_b32_e32 v18, 32, v16
	v_cmp_lt_i32_e32 vcc, v18, v17
	v_mov_b32_e32 v17, 0
	v_lshlrev_b32_e32 v22, 4, v22
	v_cndmask_b32_e32 v16, v16, v18, vcc
	v_lshlrev_b64 v[18:19], 11, v[144:145]
	v_lshl_or_b32 v18, v192, 3, v18
	v_lshlrev_b32_e32 v49, 2, v16
	v_or_b32_e32 v16, 64, v192
	v_lshl_add_u64 v[18:19], s[90:91], 0, v[18:19]
	v_lshl_add_u64 v[18:19], v[18:19], 0, s[0:1]
	v_lshlrev_b32_e32 v16, 4, v16
	v_lshlrev_b32_e32 v24, 4, v24
	v_mov_b32_e32 v50, 0x358637bd
	s_mov_b32 s2, 0xf800000
	v_mov_b32_e32 v51, 0x260
	s_mov_b32 s3, 0xeb000000
	s_movk_i32 s7, 0x7fff
	v_mov_b32_e32 v21, v17
	v_mov_b32_e32 v52, v144

.Lxb9_spin:
	global_load_dword v7, v6, s[98:99] sc1
	s_waitcnt vmcnt(0)
	v_cmp_ge_u32_e32 vcc, v7, v3
	s_cbranch_vccnz .Lxb9_done
	s_sleep 1
	s_add_i32 s100, s100, 1
	s_cmp_lt_u32 s100, 0x40000
	s_cbranch_scc1 .Lxb9_spin
.Lxb9_done:
	s_waitcnt vmcnt(0)
.LBB0_1092:
	s_or_b64 exec, exec, s[0:1]
	v_mov_b32_e32 v10, v193
	s_waitcnt lgkmcnt(0)
	s_barrier
	s_cmpk_gt_i32 s6, 0xaff
	v_readfirstlane_b32 s0, v10
	s_cbranch_scc1 .LBB0_1108
	v_lshlrev_b32_e32 v0, 4, v10
	v_add_u32_e32 v1, 0x2000, v0
	v_ashrrev_i32_e32 v2, 31, v1
	v_lshrrev_b32_e32 v2, 22, v2
	v_add_u32_e32 v2, v1, v2
	v_ashrrev_i32_e32 v8, 10, v2
	v_mul_i32_i24_e32 v2, 0x400, v8
	v_sub_u32_e32 v1, v1, v2
	v_lshrrev_b32_e32 v2, 4, v1
	v_bitop3_b32 v1, v2, v1, 32 bitop3:0x6c
	v_ashrrev_i32_e32 v2, 31, v1
	v_lshrrev_b32_e32 v2, 26, v2
	v_add_u32_e32 v2, v1, v2
	v_lshlrev_b32_e32 v3, 3, v8
	v_ashrrev_i32_e32 v9, 6, v2
	v_and_b32_e32 v3, -16, v3
	v_add_u32_e32 v3, v9, v3
	v_and_b32_e32 v4, 3, v9
	s_mov_b32 s3, 0x1fffe0
	v_lshrrev_b32_e32 v5, 2, v3
	v_lshlrev_b32_e32 v6, 1, v3
	v_and_b32_e32 v2, 0xc0, v2
	v_and_or_b32 v4, v3, s3, v4
	v_and_b32_e32 v5, 4, v5
	v_and_b32_e32 v6, 24, v6
	v_sub_u32_e32 v1, v1, v2
	v_mov_b32_e32 v2, 1
	v_or3_b32 v4, v4, v5, v6
	v_lshlrev_b32_e32 v5, 5, v8
	v_ashrrev_i16_sdwa v1, v2, sext(v1) dst_sel:DWORD dst_unused:UNUSED_PAD src0_sel:DWORD src1_sel:BYTE_0
	v_and_b32_e32 v5, 32, v5
	v_bfe_i32 v11, v1, 0, 16
	v_add_lshl_u32 v1, v5, v11, 1
	v_lshl_add_u32 v128, v4, 11, v1
	v_lshl_add_u32 v130, v3, 11, v1
	v_bfe_i32 v1, v10, 27, 1
	v_lshrrev_b32_e32 v1, 22, v1
	v_add_u32_e32 v1, v0, v1
	v_and_b32_e32 v1, 0xfffffc00, v1
	v_sub_u32_e32 v0, v0, v1
	v_lshrrev_b32_e32 v1, 4, v0
	v_ashrrev_i32_e32 v3, 31, v10
	v_bitop3_b32 v0, v1, v0, 32 bitop3:0x6c
	v_lshrrev_b32_e32 v3, 26, v3
	v_ashrrev_i32_e32 v1, 31, v0
	v_add_u32_e32 v3, v10, v3
	v_lshrrev_b32_e32 v1, 26, v1
	v_ashrrev_i32_e32 v13, 6, v3
	v_add_u32_e32 v1, v0, v1
	v_lshlrev_b32_e32 v3, 3, v13
	v_ashrrev_i32_e32 v12, 6, v1
	v_and_b32_e32 v3, -16, v3
	v_add_u32_e32 v3, v12, v3
	v_and_b32_e32 v4, 3, v12
	v_and_or_b32 v4, v3, s3, v4
	s_ashr_i32 s3, s6, 31
	s_lshr_b32 s7, s3, 29
	s_add_i32 s7, s6, s7
	s_ashr_i32 s12, s0, 6
	s_ashr_i32 s8, s7, 3
	s_and_b32 s7, s7, -8
	s_ashr_i32 s1, s0, 8
	s_lshl_b32 s2, s12, 10
	s_sub_i32 s9, s6, s7
	s_cmp_lt_i32 s9, 0
	s_movk_i32 s7, 0x161
	s_cselect_b32 s13, s7, 0x160
	s_mul_i32 s9, s9, s13
	s_add_i32 s9, s9, s8
	s_mul_hi_i32 s8, s9, 0x2e8ba2e9
	s_lshr_b32 s13, s8, 31
	s_ashr_i32 s8, s8, 5
	s_add_i32 s8, s8, s13
	s_mul_i32 s13, s8, 0xb0
	s_sub_i32 s9, s9, s13
	s_sext_i32_i16 s13, s9
	s_bfe_u32 s13, s13, 0x3001c
	s_add_i32 s13, s9, s13
	s_sext_i32_i16 s24, s13
	s_and_b32 s13, s13, 0xfff8
	s_sub_i32 s9, s9, s13
	s_sext_i32_i16 s9, s9
	s_lshl_b32 s8, s8, 11
	s_lshl_b32 s9, s9, 8
	s_add_i32 s38, s9, s8
	s_lshl_b32 s8, s24, 5
	s_ashr_i32 s39, s38, 31
	s_and_b32 s40, s8, 0xffffff00
	s_lshl_b64 s[8:9], s[38:39], 11
	v_lshrrev_b32_e32 v5, 2, v3
	v_lshlrev_b32_e32 v6, 1, v3
	v_and_b32_e32 v1, 0xc0, v1
	s_add_u32 s42, s18, s8
	v_and_b32_e32 v5, 4, v5
	v_and_b32_e32 v6, 24, v6
	v_sub_u32_e32 v0, v0, v1
	s_addc_u32 s43, s19, s9
	s_ashr_i32 s41, s40, 31
	v_or3_b32 v4, v4, v5, v6
	v_lshlrev_b32_e32 v5, 5, v13
	v_ashrrev_i16_sdwa v0, v2, sext(v0) dst_sel:DWORD dst_unused:UNUSED_PAD src0_sel:DWORD src1_sel:BYTE_0
	s_lshl_b64 s[8:9], s[40:41], 11
	v_and_b32_e32 v5, 32, v5
	v_bfe_i32 v14, v0, 0, 16
	s_add_u32 s44, s16, s8
	v_add_lshl_u32 v0, v5, v14, 1
	s_addc_u32 s45, s17, s9
	s_add_i32 s33, s2, 0
	v_lshl_add_u32 v132, v4, 11, v0
	s_add_i32 m0, s33, 0x10000
	v_lshl_add_u32 v134, v3, 11, v0
	global_load_lds_dwordx4 v132, s[44:45]
	s_add_i32 m0, s33, 0x12000
	s_add_u32 s8, s44, 0x40000
	global_load_lds_dwordx4 v128, s[44:45]
	s_addc_u32 s9, s45, 0
	s_add_i32 m0, s33, 0x14000
	s_add_i32 s34, s33, 0x2000
	global_load_lds_dwordx4 v132, s[8:9]
	s_add_i32 m0, s33, 0x16000
	v_mov_b32_e32 v137, 0
	global_load_lds_dwordx4 v128, s[8:9]
	s_mov_b32 m0, s33
	s_add_u32 s8, s42, 0x40000
	global_load_lds_dwordx4 v134, s[42:43]
	s_mov_b32 m0, s34
	s_addc_u32 s9, s43, 0
	s_add_i32 s35, s33, 0x4000
	global_load_lds_dwordx4 v130, s[42:43]
	s_mov_b32 m0, s35
	s_add_i32 s39, s33, 0x6000
	global_load_lds_dwordx4 v134, s[8:9]
	s_mov_b32 m0, s39
	v_mov_b32_e32 v133, v137
	global_load_lds_dwordx4 v130, s[8:9]
	v_mov_b32_e32 v129, v137
	v_mov_b32_e32 v135, v137
	v_mov_b32_e32 v131, v137
	s_cmp_eq_u32 s1, 1
	s_mov_b32 s41, 0
	v_lshl_add_u64 v[6:7], s[44:45], 0, v[132:133]
	v_lshl_add_u64 v[4:5], s[44:45], 0, v[128:129]
	v_lshl_add_u64 v[0:1], s[42:43], 0, v[134:135]
	s_cselect_b64 s[8:9], -1, 0
	s_cmp_lg_u32 s1, 1
	v_lshl_add_u64 v[2:3], s[42:43], 0, v[130:131]
	s_cbranch_scc1 .LBB0_1095
	s_barrier

.Lxb10_spin:
	global_load_dword v7, v6, s[98:99] sc1
	s_waitcnt vmcnt(0)
	v_cmp_ge_u32_e32 vcc, v7, v3
	s_cbranch_vccnz .Lxb10_done
	s_sleep 1
	s_add_i32 s100, s100, 1
	s_cmp_lt_u32 s100, 0x40000
	s_cbranch_scc1 .Lxb10_spin
.Lxb10_done:
	s_waitcnt vmcnt(0)
.LBB0_1160:
	s_or_b64 exec, exec, s[0:1]
	s_waitcnt lgkmcnt(0)
	s_barrier
	s_and_b64 vcc, exec, s[10:11]
	v_readfirstlane_b32 s12, v193
	s_cbranch_vccnz .LBB0_1184
	s_ashr_i32 s2, s6, 31
	s_lshr_b32 s0, s2, 29
	s_add_i32 s8, s6, s0
	s_and_b32 s0, s8, -8
	s_sub_i32 s3, s6, s0
	s_cmp_gt_i32 s3, -1
	s_cbranch_scc0 .LBB0_1163
	s_lshl_b32 s7, s3, 6
	s_ashr_i32 s8, s8, 3
	s_cbranch_execz .LBB0_1164
	s_branch .LBB0_1165

.Lxb11_spin:
	global_load_dword v7, v6, s[98:99] sc1
	s_waitcnt vmcnt(0)
	v_cmp_ge_u32_e32 vcc, v7, v3
	s_cbranch_vccnz .Lxb11_done
	s_sleep 1
	s_add_i32 s100, s100, 1
	s_cmp_lt_u32 s100, 0x40000
	s_cbranch_scc1 .Lxb11_spin
.Lxb11_done:
	s_waitcnt vmcnt(0)
.LBB0_1236:
	s_or_b64 exec, exec, s[0:1]
	s_waitcnt lgkmcnt(0)
	s_barrier
	s_and_saveexec_b64 s[0:1], s[4:5]
	s_cbranch_execz .LBB0_1239
	v_mbcnt_hi_u32_b32 v0, -1, v226
	v_and_b32_e32 v1, 64, v0
	v_add_u32_e32 v1, 64, v1
	v_xor_b32_e32 v2, 1, v0
	v_cmp_lt_i32_e32 vcc, v2, v1
	v_lshlrev_b64 v[4:5], 12, v[144:145]
	v_mov_b32_e32 v3, 0
	v_cndmask_b32_e32 v2, v0, v2, vcc
	v_lshlrev_b32_e32 v6, 2, v2
	v_xor_b32_e32 v2, 2, v0
	v_cmp_lt_i32_e32 vcc, v2, v1
	s_lshl_b32 s2, s92, 4
	s_mov_b64 s[0:1], 0x1000
	v_cndmask_b32_e32 v2, v0, v2, vcc
	v_lshlrev_b32_e32 v7, 2, v2
	v_xor_b32_e32 v2, 4, v0
	v_cmp_lt_i32_e32 vcc, v2, v1
	s_ashr_i32 s3, s2, 31
	s_lshl_b64 s[4:5], s[2:3], 12
	v_cndmask_b32_e32 v2, v0, v2, vcc
	v_lshlrev_b32_e32 v8, 2, v2
	v_xor_b32_e32 v2, 8, v0
	v_cmp_lt_i32_e32 vcc, v2, v1
	s_lshl_b64 s[6:7], s[2:3], 11
	s_mov_b64 s[8:9], 0
	v_cndmask_b32_e32 v2, v0, v2, vcc
	v_lshlrev_b32_e32 v9, 2, v2
	v_xor_b32_e32 v2, 16, v0
	v_cmp_lt_i32_e32 vcc, v2, v1
	v_mov_b32_e32 v12, 0x358637bd
	s_mov_b32 s3, 0xf800000
	v_cndmask_b32_e32 v2, v0, v2, vcc
	v_lshlrev_b32_e32 v10, 2, v2
	v_xor_b32_e32 v2, 32, v0
	v_cmp_lt_i32_e32 vcc, v2, v1
	v_mov_b32_e32 v13, 0x260
	s_movk_i32 s10, 0x7fff
	v_cndmask_b32_e32 v0, v0, v2, vcc
	v_lshlrev_b32_e32 v2, 4, v192
	v_or_b32_e32 v4, v4, v2
	v_lshlrev_b32_e32 v11, 2, v0
	v_lshl_add_u64 v[0:1], s[86:87], 0, v[2:3]
	v_lshl_add_u64 v[2:3], s[88:89], 0, v[4:5]
	v_lshlrev_b64 v[4:5], 11, v[144:145]
	v_lshl_or_b32 v4, v192, 3, v4
	v_lshl_add_u64 v[2:3], v[2:3], 0, s[0:1]
	v_lshl_add_u64 v[4:5], s[90:91], 0, v[4:5]
	s_mov_b64 s[0:1], 0x48f0000
	v_lshl_add_u64 v[4:5], v[4:5], 0, s[0:1]
